# spatial-phase LayerNorm row sums via DPP adds, on top of chained MFMA order, 64-bit clears and p-loop pipeline
# speedup vs baseline: 1.0135x; 1.0135x over previous
.LBB0_379:
	s_and_b32 s16, s62, 0xffffff80
	v_readlane_b32 s11, v254, 9
	s_lshl_b64 s[70:71], s[90:91], 1
	s_add_i32 s11, s16, s11
	v_lshl_add_u64 v[12:13], v[148:149], 0, s[70:71]
	v_mad_i64_i32 v[14:15], vcc, s11, v240, v[12:13]
	global_load_dwordx3 v[72:74], v[14:15], off
	s_or_b32 s17, s11, 1
	v_mad_i64_i32 v[14:15], vcc, s17, v240, v[12:13]
	s_or_b32 s17, s11, 2
	global_load_dwordx3 v[68:70], v[14:15], off
	v_mad_i64_i32 v[14:15], vcc, s17, v240, v[12:13]
	s_or_b32 s17, s11, 3
	global_load_dwordx3 v[64:66], v[14:15], off
	v_mad_i64_i32 v[14:15], vcc, s17, v240, v[12:13]
	s_or_b32 s17, s11, 4
	global_load_dwordx3 v[60:62], v[14:15], off
	v_mad_i64_i32 v[14:15], vcc, s17, v240, v[12:13]
	s_or_b32 s17, s11, 5
	global_load_dwordx3 v[56:58], v[14:15], off
	v_mad_i64_i32 v[14:15], vcc, s17, v240, v[12:13]
	s_or_b32 s17, s11, 6
	global_load_dwordx3 v[52:54], v[14:15], off
	v_mad_i64_i32 v[14:15], vcc, s17, v240, v[12:13]
	s_or_b32 s17, s11, 7
	global_load_dwordx3 v[48:50], v[14:15], off
	v_mad_i64_i32 v[14:15], vcc, s17, v240, v[12:13]
	s_or_b32 s17, s11, 8
	global_load_dwordx3 v[44:46], v[14:15], off
	v_mad_i64_i32 v[14:15], vcc, s17, v240, v[12:13]
	s_or_b32 s17, s11, 9
	global_load_dwordx3 v[40:42], v[14:15], off
	v_mad_i64_i32 v[14:15], vcc, s17, v240, v[12:13]
	s_or_b32 s17, s11, 10
	global_load_dwordx3 v[36:38], v[14:15], off
	v_mad_i64_i32 v[14:15], vcc, s17, v240, v[12:13]
	s_or_b32 s17, s11, 11
	global_load_dwordx3 v[32:34], v[14:15], off
	v_mad_i64_i32 v[14:15], vcc, s17, v240, v[12:13]
	s_or_b32 s17, s11, 12
	global_load_dwordx3 v[28:30], v[14:15], off
	v_mad_i64_i32 v[14:15], vcc, s17, v240, v[12:13]
	s_or_b32 s17, s11, 13
	global_load_dwordx3 v[24:26], v[14:15], off
	v_mad_i64_i32 v[14:15], vcc, s17, v240, v[12:13]
	s_or_b32 s17, s11, 14
	global_load_dwordx3 v[20:22], v[14:15], off
	v_mad_i64_i32 v[14:15], vcc, s17, v240, v[12:13]
	global_load_dwordx3 v[16:18], v[14:15], off
	s_or_b32 s11, s11, 15
	v_mad_i64_i32 v[12:13], vcc, s11, v240, v[12:13]
	global_load_dwordx3 v[12:14], v[12:13], off
	v_add_u32_e32 v140, 0, v173
	s_waitcnt vmcnt(15)
	v_lshlrev_b32_e32 v77, 16, v72
	v_lshlrev_b32_e32 v76, 16, v74
	v_and_b32_e32 v75, 0xffff0000, v72
	v_and_b32_e32 v74, 0xffff0000, v74
	v_lshlrev_b32_e32 v80, 16, v73
	v_and_b32_e32 v73, 0xffff0000, v73
	v_pk_add_f32 v[78:79], v[76:77], v[74:75]
	v_add_f32_e32 v15, v73, v80
	v_add_f32_e32 v15, v79, v15
	v_add_f32_e32 v15, v78, v15
	v_mov_b32_e32 v81, v73
	v_pk_mul_f32 v[78:79], v[80:81], v[80:81]
	v_pk_mul_f32 v[82:83], v[74:75], v[74:75]
	v_add_f32_e32 v19, v78, v79
	s_waitcnt lgkmcnt(0)
	s_nop 1
	v_add_f32_dpp v15, v15, v15 quad_perm:[1,0,3,2] row_mask:0xf bank_mask:0xf
	v_pk_fma_f32 v[82:83], v[76:77], v[76:77], v[82:83]
	v_and_b32_e32 v72, s0, v72
	v_add_f32_e32 v19, v83, v19
	v_add_f32_e32 v19, v82, v19
	s_waitcnt lgkmcnt(0)
	s_nop 1
	v_add_f32_dpp v15, v15, v15 quad_perm:[2,3,0,1] row_mask:0xf bank_mask:0xf
	s_waitcnt vmcnt(14)
	v_and_b32_e32 v71, 0xffff0000, v68
	s_waitcnt lgkmcnt(0)
	s_nop 1
	v_add_f32_dpp v15, v15, v15 row_half_mirror row_mask:0xf bank_mask:0xf
	s_waitcnt lgkmcnt(0)
	s_nop 1
	v_add_f32_dpp v15, v15, v15 row_mirror row_mask:0xf bank_mask:0xf
	ds_swizzle_b32 v23, v15 offset:swizzle(SWAP,16)
	s_waitcnt lgkmcnt(0)
	v_add_f32_e32 v79, v15, v23
	v_mov_b32_e32 v83, v79
	s_nop 1
	v_permlane32_swap_b32_e32 v79, v83
	s_waitcnt lgkmcnt(0)
	s_nop 1
	v_add_f32_dpp v15, v19, v19 quad_perm:[1,0,3,2] row_mask:0xf bank_mask:0xf
	s_waitcnt lgkmcnt(0)
	s_nop 1
	v_add_f32_dpp v15, v15, v15 quad_perm:[2,3,0,1] row_mask:0xf bank_mask:0xf
	s_waitcnt lgkmcnt(0)
	s_nop 1
	v_add_f32_dpp v15, v15, v15 row_half_mirror row_mask:0xf bank_mask:0xf
	s_waitcnt lgkmcnt(0)
	s_nop 1
	v_add_f32_dpp v15, v15, v15 row_mirror row_mask:0xf bank_mask:0xf
	ds_swizzle_b32 v19, v15 offset:swizzle(SWAP,16)
	s_waitcnt lgkmcnt(0)
	v_add_f32_e32 v78, v15, v19
	v_mov_b32_e32 v82, v78
	s_nop 1
	v_permlane32_swap_b32_e32 v78, v82
	v_pk_add_f32 v[78:79], v[78:79], v[82:83]
	s_nop 0
	v_pk_mul_f32 v[82:83], v[78:79], s[88:89] op_sel_hi:[1,0]
	v_pk_fma_f32 v[72:73], v[78:79], s[88:89], v[72:73] op_sel_hi:[1,0,1] neg_lo:[1,0,0] neg_hi:[1,0,0]
	v_fma_f32 v15, -v83, v83, v82
	v_max_f32_e32 v15, 0, v15
	v_add_f32_e32 v15, 0x358637bd, v15
	v_rsq_f32_e32 v15, v15
	v_sub_f32_e32 v19, v77, v83
	v_sub_f32_e32 v39, v74, v83
	v_lshlrev_b32_e32 v72, 16, v70
	v_mul_f32_e32 v19, v19, v15
	v_fma_f32 v35, v8, v19, v4
	v_sub_f32_e32 v19, v75, v83
	v_mul_f32_e32 v19, v19, v15
	v_fma_f32 v31, v9, v19, v5
	v_sub_f32_e32 v19, v80, v83
	v_mul_f32_e32 v19, v19, v15
	v_fma_f32 v27, v10, v19, v6
	v_mul_f32_e32 v19, v73, v15
	v_fma_f32 v23, v11, v19, v7
	v_sub_f32_e32 v19, v76, v83
	v_lshlrev_b32_e32 v73, 16, v68
	v_and_b32_e32 v70, 0xffff0000, v70
	v_lshlrev_b32_e32 v74, 16, v69
	v_and_b32_e32 v69, 0xffff0000, v69
	v_mul_f32_e32 v19, v19, v15
	v_mul_f32_e32 v15, v39, v15
	v_pk_add_f32 v[76:77], v[72:73], v[70:71]
	v_add_f32_e32 v39, v69, v74
	v_add_f32_e32 v39, v77, v39
	v_add_f32_e32 v39, v76, v39
	v_mov_b32_e32 v75, v69
	v_pk_mul_f32 v[76:77], v[74:75], v[74:75]
	v_pk_mul_f32 v[78:79], v[70:71], v[70:71]
	v_add_f32_e32 v43, v76, v77
	s_waitcnt lgkmcnt(0)
	s_nop 1
	v_add_f32_dpp v39, v39, v39 quad_perm:[1,0,3,2] row_mask:0xf bank_mask:0xf
	v_pk_fma_f32 v[78:79], v[72:73], v[72:73], v[78:79]
	v_and_b32_e32 v68, s0, v68
	v_add_f32_e32 v43, v79, v43
	v_add_f32_e32 v43, v78, v43
	s_waitcnt lgkmcnt(0)
	s_nop 1
	v_add_f32_dpp v39, v39, v39 quad_perm:[2,3,0,1] row_mask:0xf bank_mask:0xf
	v_fma_f32 v19, v0, v19, v2
	v_fma_f32 v15, v1, v15, v3
	s_waitcnt lgkmcnt(0)
	s_nop 1
	v_add_f32_dpp v39, v39, v39 row_half_mirror row_mask:0xf bank_mask:0xf
	s_waitcnt lgkmcnt(0)
	s_nop 1
	v_add_f32_dpp v39, v39, v39 row_mirror row_mask:0xf bank_mask:0xf
	ds_swizzle_b32 v47, v39 offset:swizzle(SWAP,16)
	s_waitcnt lgkmcnt(0)
	v_add_f32_e32 v77, v39, v47
	v_mov_b32_e32 v79, v77
	s_nop 1
	v_permlane32_swap_b32_e32 v77, v79
	s_waitcnt lgkmcnt(0)
	s_nop 1
	v_add_f32_dpp v39, v43, v43 quad_perm:[1,0,3,2] row_mask:0xf bank_mask:0xf
	s_waitcnt lgkmcnt(0)
	s_nop 1
	v_add_f32_dpp v39, v39, v39 quad_perm:[2,3,0,1] row_mask:0xf bank_mask:0xf
	s_waitcnt lgkmcnt(0)
	s_nop 1
	v_add_f32_dpp v39, v39, v39 row_half_mirror row_mask:0xf bank_mask:0xf
	s_waitcnt lgkmcnt(0)
	s_nop 1
	v_add_f32_dpp v39, v39, v39 row_mirror row_mask:0xf bank_mask:0xf
	ds_swizzle_b32 v43, v39 offset:swizzle(SWAP,16)
	s_waitcnt lgkmcnt(0)
	v_add_f32_e32 v76, v39, v43
	v_mov_b32_e32 v78, v76
	s_nop 1
	v_permlane32_swap_b32_e32 v76, v78
	v_pk_add_f32 v[76:77], v[76:77], v[78:79]
	s_nop 0
	v_pk_mul_f32 v[78:79], v[76:77], s[88:89] op_sel_hi:[1,0]
	v_pk_fma_f32 v[68:69], v[76:77], s[88:89], v[68:69] op_sel_hi:[1,0,1] neg_lo:[1,0,0] neg_hi:[1,0,0]
	v_fma_f32 v39, -v79, v79, v78
	v_max_f32_e32 v39, 0, v39
	v_add_f32_e32 v39, 0x358637bd, v39
	v_rsq_f32_e32 v39, v39
	v_sub_f32_e32 v43, v73, v79
	v_sub_f32_e32 v63, v70, v79
	s_waitcnt vmcnt(13)
	v_lshlrev_b32_e32 v70, 16, v66
	v_mul_f32_e32 v43, v43, v39
	v_fma_f32 v59, v8, v43, v4
	v_sub_f32_e32 v43, v71, v79
	v_mul_f32_e32 v43, v43, v39
	v_fma_f32 v55, v9, v43, v5
	v_sub_f32_e32 v43, v74, v79
	v_mul_f32_e32 v43, v43, v39
	v_fma_f32 v51, v10, v43, v6
	v_mul_f32_e32 v43, v69, v39
	v_fma_f32 v47, v11, v43, v7
	v_sub_f32_e32 v43, v72, v79
	v_lshlrev_b32_e32 v71, 16, v64
	v_and_b32_e32 v73, 0xffff0000, v64
	v_and_b32_e32 v72, 0xffff0000, v66
	v_lshlrev_b32_e32 v74, 16, v65
	v_and_b32_e32 v65, 0xffff0000, v65
	v_mul_f32_e32 v43, v43, v39
	v_mul_f32_e32 v39, v63, v39
	v_pk_add_f32 v[66:67], v[70:71], v[72:73]
	v_add_f32_e32 v63, v65, v74
	v_mov_b32_e32 v75, v65
	v_add_f32_e32 v63, v67, v63
	v_add_f32_e32 v63, v66, v63
	v_pk_mul_f32 v[66:67], v[74:75], v[74:75]
	v_pk_mul_f32 v[68:69], v[72:73], v[72:73]
	v_add_f32_e32 v66, v66, v67
	v_pk_fma_f32 v[68:69], v[70:71], v[70:71], v[68:69]
	v_and_b32_e32 v64, s0, v64
	v_add_f32_e32 v66, v69, v66
	v_add_f32_e32 v66, v68, v66
	s_waitcnt lgkmcnt(0)
	s_nop 1
	v_add_f32_dpp v63, v63, v63 quad_perm:[1,0,3,2] row_mask:0xf bank_mask:0xf
	s_waitcnt vmcnt(12)
	v_and_b32_e32 v75, 0xffff0000, v60
	v_fma_f32 v43, v0, v43, v2
	v_fma_f32 v39, v1, v39, v3
	s_waitcnt lgkmcnt(0)
	s_nop 1
	v_add_f32_dpp v63, v63, v63 quad_perm:[2,3,0,1] row_mask:0xf bank_mask:0xf
	s_waitcnt lgkmcnt(0)
	s_nop 1
	v_add_f32_dpp v63, v63, v63 row_half_mirror row_mask:0xf bank_mask:0xf
	s_waitcnt lgkmcnt(0)
	s_nop 1
	v_add_f32_dpp v63, v63, v63 row_mirror row_mask:0xf bank_mask:0xf
	ds_swizzle_b32 v67, v63 offset:swizzle(SWAP,16)
	s_waitcnt lgkmcnt(0)
	v_add_f32_e32 v67, v63, v67
	v_mov_b32_e32 v69, v67
	s_nop 1
	v_permlane32_swap_b32_e32 v67, v69
	s_waitcnt lgkmcnt(0)
	s_nop 1
	v_add_f32_dpp v63, v66, v66 quad_perm:[1,0,3,2] row_mask:0xf bank_mask:0xf
	s_waitcnt lgkmcnt(0)
	s_nop 1
	v_add_f32_dpp v63, v63, v63 quad_perm:[2,3,0,1] row_mask:0xf bank_mask:0xf
	s_waitcnt lgkmcnt(0)
	s_nop 1
	v_add_f32_dpp v63, v63, v63 row_half_mirror row_mask:0xf bank_mask:0xf
	s_waitcnt lgkmcnt(0)
	s_nop 1
	v_add_f32_dpp v63, v63, v63 row_mirror row_mask:0xf bank_mask:0xf
	ds_swizzle_b32 v66, v63 offset:swizzle(SWAP,16)
	s_waitcnt lgkmcnt(0)
	v_add_f32_e32 v66, v63, v66
	v_mov_b32_e32 v68, v66
	s_nop 1
	v_permlane32_swap_b32_e32 v66, v68
	v_pk_add_f32 v[76:77], v[66:67], v[68:69]
	s_nop 0
	v_pk_mul_f32 v[68:69], v[76:77], s[88:89] op_sel_hi:[1,0]
	v_pk_fma_f32 v[64:65], v[76:77], s[88:89], v[64:65] op_sel_hi:[1,0,1] neg_lo:[1,0,0] neg_hi:[1,0,0]
	v_fma_f32 v63, -v69, v69, v68
	v_max_f32_e32 v63, 0, v63
	v_add_f32_e32 v63, 0x358637bd, v63
	v_rsq_f32_e32 v63, v63
	v_sub_f32_e32 v66, v71, v69
	v_lshlrev_b32_e32 v76, 16, v61
	v_and_b32_e32 v61, 0xffff0000, v61
	v_mul_f32_e32 v66, v66, v63
	v_fma_f32 v68, v8, v66, v4
	v_sub_f32_e32 v66, v73, v69
	v_mul_f32_e32 v66, v66, v63
	v_mul_f32_e32 v64, v65, v63
	v_fma_f32 v67, v9, v66, v5
	v_sub_f32_e32 v66, v74, v69
	v_fma_f32 v65, v11, v64, v7
	v_sub_f32_e32 v64, v70, v69
	v_sub_f32_e32 v69, v72, v69
	v_lshlrev_b32_e32 v73, 16, v60
	v_lshlrev_b32_e32 v72, 16, v62
	v_and_b32_e32 v74, 0xffff0000, v62
	v_pk_add_f32 v[70:71], v[72:73], v[74:75]
	v_add_f32_e32 v62, v61, v76
	v_mov_b32_e32 v77, v61
	v_add_f32_e32 v62, v71, v62
	v_add_f32_e32 v62, v70, v62
	v_pk_mul_f32 v[70:71], v[76:77], v[76:77]
	v_mul_f32_e32 v66, v66, v63
	v_mul_f32_e32 v64, v64, v63
	v_mul_f32_e32 v63, v69, v63
	v_add_f32_e32 v69, v70, v71
	v_pk_mul_f32 v[78:79], v[74:75], v[74:75]
	v_and_b32_e32 v60, s0, v60
	v_pk_fma_f32 v[78:79], v[72:73], v[72:73], v[78:79]
	v_fma_f32 v66, v10, v66, v6
	s_waitcnt lgkmcnt(0)
	s_nop 1
	v_add_f32_dpp v62, v62, v62 quad_perm:[1,0,3,2] row_mask:0xf bank_mask:0xf
	v_add_f32_e32 v69, v79, v69
	v_add_f32_e32 v69, v78, v69
	v_fma_f32 v64, v0, v64, v2
	v_fma_f32 v63, v1, v63, v3
	s_waitcnt lgkmcnt(0)
	s_nop 1
	v_add_f32_dpp v62, v62, v62 quad_perm:[2,3,0,1] row_mask:0xf bank_mask:0xf
	s_waitcnt lgkmcnt(0)
	s_nop 1
	v_add_f32_dpp v62, v62, v62 row_half_mirror row_mask:0xf bank_mask:0xf
	s_waitcnt lgkmcnt(0)
	s_nop 1
	v_add_f32_dpp v62, v62, v62 row_mirror row_mask:0xf bank_mask:0xf
	ds_swizzle_b32 v70, v62 offset:swizzle(SWAP,16)
	s_waitcnt lgkmcnt(0)
	v_add_f32_e32 v71, v62, v70
	v_mov_b32_e32 v79, v71
	s_nop 1
	v_permlane32_swap_b32_e32 v71, v79
	s_waitcnt lgkmcnt(0)
	s_nop 1
	v_add_f32_dpp v62, v69, v69 quad_perm:[1,0,3,2] row_mask:0xf bank_mask:0xf
	s_waitcnt lgkmcnt(0)
	s_nop 1
	v_add_f32_dpp v62, v62, v62 quad_perm:[2,3,0,1] row_mask:0xf bank_mask:0xf
	s_waitcnt lgkmcnt(0)
	s_nop 1
	v_add_f32_dpp v62, v62, v62 row_half_mirror row_mask:0xf bank_mask:0xf
	s_waitcnt lgkmcnt(0)
	s_nop 1
	v_add_f32_dpp v62, v62, v62 row_mirror row_mask:0xf bank_mask:0xf
	ds_swizzle_b32 v69, v62 offset:swizzle(SWAP,16)
	s_waitcnt lgkmcnt(0)
	v_add_f32_e32 v70, v62, v69
	v_mov_b32_e32 v78, v70
	s_nop 1
	v_permlane32_swap_b32_e32 v70, v78
	v_pk_add_f32 v[78:79], v[70:71], v[78:79]
	s_nop 0
	v_pk_mul_f32 v[80:81], v[78:79], s[88:89] op_sel_hi:[1,0]
	v_pk_fma_f32 v[60:61], v[78:79], s[88:89], v[60:61] op_sel_hi:[1,0,1] neg_lo:[1,0,0] neg_hi:[1,0,0]
	v_fma_f32 v62, -v81, v81, v80
	v_max_f32_e32 v62, 0, v62
	v_add_f32_e32 v62, 0x358637bd, v62
	v_rsq_f32_e32 v77, v62
	v_sub_f32_e32 v62, v73, v81
	s_waitcnt vmcnt(11)
	v_and_b32_e32 v79, 0xffff0000, v56
	v_and_b32_e32 v78, 0xffff0000, v58
	v_mul_f32_e32 v62, v62, v77
	v_fma_f32 v71, v8, v62, v4
	v_sub_f32_e32 v62, v75, v81
	v_mul_f32_e32 v62, v62, v77
	v_fma_f32 v70, v9, v62, v5
	v_sub_f32_e32 v62, v76, v81
	v_mul_f32_e32 v62, v62, v77
	v_mul_f32_e32 v60, v61, v77
	v_fma_f32 v69, v10, v62, v6
	v_fma_f32 v62, v11, v60, v7
	v_sub_f32_e32 v60, v72, v81
	v_mul_f32_e32 v60, v60, v77
	v_fma_f32 v61, v0, v60, v2
	v_sub_f32_e32 v60, v74, v81
	v_mul_f32_e32 v60, v60, v77
	v_lshlrev_b32_e32 v77, 16, v56
	v_lshlrev_b32_e32 v76, 16, v58
	v_lshlrev_b32_e32 v80, 16, v57
	v_and_b32_e32 v57, 0xffff0000, v57
	v_pk_add_f32 v[72:73], v[76:77], v[78:79]
	v_add_f32_e32 v58, v57, v80
	v_mov_b32_e32 v81, v57
	v_add_f32_e32 v58, v73, v58
	v_add_f32_e32 v58, v72, v58
	v_pk_mul_f32 v[72:73], v[80:81], v[80:81]
	v_pk_mul_f32 v[74:75], v[78:79], v[78:79]
	v_add_f32_e32 v72, v72, v73
	v_pk_fma_f32 v[74:75], v[76:77], v[76:77], v[74:75]
	v_and_b32_e32 v56, s0, v56
	v_add_f32_e32 v72, v75, v72
	v_add_f32_e32 v72, v74, v72
	s_waitcnt lgkmcnt(0)
	s_nop 1
	v_add_f32_dpp v58, v58, v58 quad_perm:[1,0,3,2] row_mask:0xf bank_mask:0xf
	v_fma_f32 v60, v1, v60, v3
	s_waitcnt lgkmcnt(0)
	s_nop 1
	v_add_f32_dpp v58, v58, v58 quad_perm:[2,3,0,1] row_mask:0xf bank_mask:0xf
	s_waitcnt lgkmcnt(0)
	s_nop 1
	v_add_f32_dpp v58, v58, v58 row_half_mirror row_mask:0xf bank_mask:0xf
	s_waitcnt lgkmcnt(0)
	s_nop 1
	v_add_f32_dpp v58, v58, v58 row_mirror row_mask:0xf bank_mask:0xf
	ds_swizzle_b32 v73, v58 offset:swizzle(SWAP,16)
	s_waitcnt lgkmcnt(0)
	v_add_f32_e32 v73, v58, v73
	v_mov_b32_e32 v75, v73
	s_nop 1
	v_permlane32_swap_b32_e32 v73, v75
	s_waitcnt lgkmcnt(0)
	s_nop 1
	v_add_f32_dpp v58, v72, v72 quad_perm:[1,0,3,2] row_mask:0xf bank_mask:0xf
	s_waitcnt lgkmcnt(0)
	s_nop 1
	v_add_f32_dpp v58, v58, v58 quad_perm:[2,3,0,1] row_mask:0xf bank_mask:0xf
	s_waitcnt lgkmcnt(0)
	s_nop 1
	v_add_f32_dpp v58, v58, v58 row_half_mirror row_mask:0xf bank_mask:0xf
	s_waitcnt lgkmcnt(0)
	s_nop 1
	v_add_f32_dpp v58, v58, v58 row_mirror row_mask:0xf bank_mask:0xf
	ds_swizzle_b32 v72, v58 offset:swizzle(SWAP,16)
	s_waitcnt lgkmcnt(0)
	v_add_f32_e32 v72, v58, v72
	v_mov_b32_e32 v74, v72
	s_nop 1
	v_permlane32_swap_b32_e32 v72, v74
	v_pk_add_f32 v[82:83], v[72:73], v[74:75]
	s_nop 0
	v_pk_mul_f32 v[74:75], v[82:83], s[88:89] op_sel_hi:[1,0]
	v_pk_fma_f32 v[56:57], v[82:83], s[88:89], v[56:57] op_sel_hi:[1,0,1] neg_lo:[1,0,0] neg_hi:[1,0,0]
	v_fma_f32 v58, -v75, v75, v74
	v_max_f32_e32 v58, 0, v58
	v_add_f32_e32 v58, 0x358637bd, v58
	v_rsq_f32_e32 v81, v58
	v_sub_f32_e32 v58, v77, v75
	s_waitcnt vmcnt(10)
	v_lshlrev_b32_e32 v82, 16, v53
	v_and_b32_e32 v53, 0xffff0000, v53
	v_mul_f32_e32 v58, v58, v81
	v_fma_f32 v74, v8, v58, v4
	v_sub_f32_e32 v58, v79, v75
	v_mul_f32_e32 v58, v58, v81
	v_fma_f32 v73, v9, v58, v5
	v_sub_f32_e32 v58, v80, v75
	v_mul_f32_e32 v58, v58, v81
	v_mul_f32_e32 v56, v57, v81
	v_fma_f32 v72, v10, v58, v6
	v_fma_f32 v58, v11, v56, v7
	v_sub_f32_e32 v56, v76, v75
	v_mul_f32_e32 v56, v56, v81
	v_fma_f32 v57, v0, v56, v2
	v_sub_f32_e32 v56, v78, v75
	v_mul_f32_e32 v56, v56, v81
	v_lshlrev_b32_e32 v79, 16, v52
	v_lshlrev_b32_e32 v78, 16, v54
	v_and_b32_e32 v81, 0xffff0000, v52
	v_and_b32_e32 v80, 0xffff0000, v54
	v_pk_add_f32 v[76:77], v[78:79], v[80:81]
	v_add_f32_e32 v54, v53, v82
	v_mov_b32_e32 v83, v53
	v_add_f32_e32 v54, v77, v54
	v_add_f32_e32 v54, v76, v54
	v_pk_mul_f32 v[76:77], v[82:83], v[82:83]
	v_pk_mul_f32 v[84:85], v[80:81], v[80:81]
	v_add_f32_e32 v75, v76, v77
	v_pk_fma_f32 v[84:85], v[78:79], v[78:79], v[84:85]
	v_and_b32_e32 v52, s0, v52
	v_add_f32_e32 v75, v85, v75
	v_add_f32_e32 v75, v84, v75
	s_waitcnt lgkmcnt(0)
	s_nop 1
	v_add_f32_dpp v54, v54, v54 quad_perm:[1,0,3,2] row_mask:0xf bank_mask:0xf
	v_fma_f32 v56, v1, v56, v3
	s_waitcnt lgkmcnt(0)
	s_nop 1
	v_add_f32_dpp v54, v54, v54 quad_perm:[2,3,0,1] row_mask:0xf bank_mask:0xf
	s_waitcnt lgkmcnt(0)
	s_nop 1
	v_add_f32_dpp v54, v54, v54 row_half_mirror row_mask:0xf bank_mask:0xf
	s_waitcnt lgkmcnt(0)
	s_nop 1
	v_add_f32_dpp v54, v54, v54 row_mirror row_mask:0xf bank_mask:0xf
	ds_swizzle_b32 v76, v54 offset:swizzle(SWAP,16)
	s_waitcnt lgkmcnt(0)
	v_add_f32_e32 v77, v54, v76
	v_mov_b32_e32 v85, v77
	s_nop 1
	v_permlane32_swap_b32_e32 v77, v85
	s_waitcnt lgkmcnt(0)
	s_nop 1
	v_add_f32_dpp v54, v75, v75 quad_perm:[1,0,3,2] row_mask:0xf bank_mask:0xf
	s_waitcnt lgkmcnt(0)
	s_nop 1
	v_add_f32_dpp v54, v54, v54 quad_perm:[2,3,0,1] row_mask:0xf bank_mask:0xf
	s_waitcnt lgkmcnt(0)
	s_nop 1
	v_add_f32_dpp v54, v54, v54 row_half_mirror row_mask:0xf bank_mask:0xf
	s_waitcnt lgkmcnt(0)
	s_nop 1
	v_add_f32_dpp v54, v54, v54 row_mirror row_mask:0xf bank_mask:0xf
	ds_swizzle_b32 v75, v54 offset:swizzle(SWAP,16)
	s_waitcnt lgkmcnt(0)
	v_add_f32_e32 v76, v54, v75
	v_mov_b32_e32 v84, v76
	s_nop 1
	v_permlane32_swap_b32_e32 v76, v84
	v_pk_add_f32 v[84:85], v[76:77], v[84:85]
	s_nop 0
	v_pk_mul_f32 v[86:87], v[84:85], s[88:89] op_sel_hi:[1,0]
	v_pk_fma_f32 v[52:53], v[84:85], s[88:89], v[52:53] op_sel_hi:[1,0,1] neg_lo:[1,0,0] neg_hi:[1,0,0]
	v_fma_f32 v54, -v87, v87, v86
	v_max_f32_e32 v54, 0, v54
	v_add_f32_e32 v54, 0x358637bd, v54
	v_rsq_f32_e32 v83, v54
	v_sub_f32_e32 v54, v79, v87
	s_waitcnt vmcnt(9)
	v_lshlrev_b32_e32 v79, 16, v48
	v_lshlrev_b32_e32 v84, 16, v49
	v_mul_f32_e32 v54, v54, v83
	v_fma_f32 v77, v8, v54, v4
	v_sub_f32_e32 v54, v81, v87
	v_mul_f32_e32 v54, v54, v83
	v_fma_f32 v76, v9, v54, v5
	v_sub_f32_e32 v54, v82, v87
	v_mul_f32_e32 v54, v54, v83
	v_mul_f32_e32 v52, v53, v83
	v_fma_f32 v75, v10, v54, v6
	v_fma_f32 v54, v11, v52, v7
	v_sub_f32_e32 v52, v78, v87
	v_mul_f32_e32 v52, v52, v83
	v_fma_f32 v53, v0, v52, v2
	v_sub_f32_e32 v52, v80, v87
	v_lshlrev_b32_e32 v78, 16, v50
	v_and_b32_e32 v81, 0xffff0000, v48
	v_and_b32_e32 v80, 0xffff0000, v50
	v_and_b32_e32 v49, 0xffff0000, v49
	v_mul_f32_e32 v52, v52, v83
	v_pk_add_f32 v[82:83], v[78:79], v[80:81]
	v_add_f32_e32 v50, v49, v84
	v_mov_b32_e32 v85, v49
	v_add_f32_e32 v50, v83, v50
	v_add_f32_e32 v50, v82, v50
	v_pk_mul_f32 v[82:83], v[84:85], v[84:85]
	v_pk_mul_f32 v[86:87], v[80:81], v[80:81]
	v_add_f32_e32 v82, v82, v83
	v_pk_fma_f32 v[86:87], v[78:79], v[78:79], v[86:87]
	v_and_b32_e32 v48, s0, v48
	v_add_f32_e32 v82, v87, v82
	v_add_f32_e32 v82, v86, v82
	s_waitcnt lgkmcnt(0)
	s_nop 1
	v_add_f32_dpp v50, v50, v50 quad_perm:[1,0,3,2] row_mask:0xf bank_mask:0xf
	v_fma_f32 v52, v1, v52, v3
	s_waitcnt lgkmcnt(0)
	s_nop 1
	v_add_f32_dpp v50, v50, v50 quad_perm:[2,3,0,1] row_mask:0xf bank_mask:0xf
	s_waitcnt lgkmcnt(0)
	s_nop 1
	v_add_f32_dpp v50, v50, v50 row_half_mirror row_mask:0xf bank_mask:0xf
	s_waitcnt lgkmcnt(0)
	s_nop 1
	v_add_f32_dpp v50, v50, v50 row_mirror row_mask:0xf bank_mask:0xf
	ds_swizzle_b32 v83, v50 offset:swizzle(SWAP,16)
	s_waitcnt lgkmcnt(0)
	v_add_f32_e32 v83, v50, v83
	v_mov_b32_e32 v87, v83
	s_nop 1
	v_permlane32_swap_b32_e32 v83, v87
	s_waitcnt lgkmcnt(0)
	s_nop 1
	v_add_f32_dpp v50, v82, v82 quad_perm:[1,0,3,2] row_mask:0xf bank_mask:0xf
	s_waitcnt lgkmcnt(0)
	s_nop 1
	v_add_f32_dpp v50, v50, v50 quad_perm:[2,3,0,1] row_mask:0xf bank_mask:0xf
	s_waitcnt lgkmcnt(0)
	s_nop 1
	v_add_f32_dpp v50, v50, v50 row_half_mirror row_mask:0xf bank_mask:0xf
	s_waitcnt lgkmcnt(0)
	s_nop 1
	v_add_f32_dpp v50, v50, v50 row_mirror row_mask:0xf bank_mask:0xf
	ds_swizzle_b32 v82, v50 offset:swizzle(SWAP,16)
	s_waitcnt lgkmcnt(0)
	v_add_f32_e32 v82, v50, v82
	v_mov_b32_e32 v86, v82
	s_nop 1
	v_permlane32_swap_b32_e32 v82, v86
	v_pk_add_f32 v[82:83], v[82:83], v[86:87]
	s_nop 0
	v_pk_mul_f32 v[86:87], v[82:83], s[88:89] op_sel_hi:[1,0]
	v_pk_fma_f32 v[48:49], v[82:83], s[88:89], v[48:49] op_sel_hi:[1,0,1] neg_lo:[1,0,0] neg_hi:[1,0,0]
	v_fma_f32 v50, -v87, v87, v86
	v_max_f32_e32 v50, 0, v50
	v_add_f32_e32 v50, 0x358637bd, v50
	v_rsq_f32_e32 v50, v50
	v_sub_f32_e32 v79, v79, v87
	s_waitcnt vmcnt(8)
	v_lshlrev_b32_e32 v82, 16, v45
	v_and_b32_e32 v45, 0xffff0000, v45
	v_mul_f32_e32 v79, v79, v50
	v_mul_f32_e32 v48, v49, v50
	v_fma_f32 v86, v8, v79, v4
	v_sub_f32_e32 v79, v81, v87
	v_fma_f32 v90, v11, v48, v7
	v_sub_f32_e32 v48, v78, v87
	v_mul_f32_e32 v79, v79, v50
	v_mul_f32_e32 v48, v48, v50
	v_fma_f32 v88, v9, v79, v5
	v_sub_f32_e32 v79, v84, v87
	v_fma_f32 v91, v0, v48, v2
	v_sub_f32_e32 v48, v80, v87
	v_mul_f32_e32 v79, v79, v50
	v_mul_f32_e32 v48, v48, v50
	v_fma_f32 v89, v10, v79, v6
	v_fma_f32 v87, v1, v48, v3
	v_lshlrev_b32_e32 v49, 16, v44
	v_lshlrev_b32_e32 v48, 16, v46
	v_and_b32_e32 v79, 0xffff0000, v44
	v_and_b32_e32 v78, 0xffff0000, v46
	v_pk_add_f32 v[80:81], v[48:49], v[78:79]
	v_add_f32_e32 v46, v45, v82
	v_mov_b32_e32 v83, v45
	v_add_f32_e32 v46, v81, v46
	v_add_f32_e32 v46, v80, v46
	v_pk_mul_f32 v[80:81], v[82:83], v[82:83]
	v_pk_mul_f32 v[84:85], v[78:79], v[78:79]
	v_add_f32_e32 v50, v80, v81
	v_pk_fma_f32 v[84:85], v[48:49], v[48:49], v[84:85]
	v_and_b32_e32 v44, s0, v44
	v_add_f32_e32 v50, v85, v50
	v_add_f32_e32 v50, v84, v50
	s_waitcnt lgkmcnt(0)
	s_nop 1
	v_add_f32_dpp v46, v46, v46 quad_perm:[1,0,3,2] row_mask:0xf bank_mask:0xf
	s_waitcnt lgkmcnt(0)
	s_nop 1
	v_add_f32_dpp v46, v46, v46 quad_perm:[2,3,0,1] row_mask:0xf bank_mask:0xf
	s_waitcnt lgkmcnt(0)
	s_nop 1
	v_add_f32_dpp v46, v46, v46 row_half_mirror row_mask:0xf bank_mask:0xf
	s_waitcnt lgkmcnt(0)
	s_nop 1
	v_add_f32_dpp v46, v46, v46 row_mirror row_mask:0xf bank_mask:0xf
	ds_swizzle_b32 v80, v46 offset:swizzle(SWAP,16)
	s_waitcnt lgkmcnt(0)
	v_add_f32_e32 v81, v46, v80
	v_mov_b32_e32 v85, v81
	s_nop 1
	v_permlane32_swap_b32_e32 v81, v85
	s_waitcnt lgkmcnt(0)
	s_nop 1
	v_add_f32_dpp v46, v50, v50 quad_perm:[1,0,3,2] row_mask:0xf bank_mask:0xf
	s_waitcnt lgkmcnt(0)
	s_nop 1
	v_add_f32_dpp v46, v46, v46 quad_perm:[2,3,0,1] row_mask:0xf bank_mask:0xf
	s_waitcnt lgkmcnt(0)
	s_nop 1
	v_add_f32_dpp v46, v46, v46 row_half_mirror row_mask:0xf bank_mask:0xf
	s_waitcnt lgkmcnt(0)
	s_nop 1
	v_add_f32_dpp v46, v46, v46 row_mirror row_mask:0xf bank_mask:0xf
	ds_swizzle_b32 v50, v46 offset:swizzle(SWAP,16)
	s_waitcnt lgkmcnt(0)
	v_add_f32_e32 v80, v46, v50
	v_mov_b32_e32 v84, v80
	s_nop 1
	v_permlane32_swap_b32_e32 v80, v84
	v_pk_add_f32 v[80:81], v[80:81], v[84:85]
	s_nop 0
	v_pk_mul_f32 v[84:85], v[80:81], s[88:89] op_sel_hi:[1,0]
	v_pk_fma_f32 v[44:45], v[80:81], s[88:89], v[44:45] op_sel_hi:[1,0,1] neg_lo:[1,0,0] neg_hi:[1,0,0]
	v_fma_f32 v46, -v85, v85, v84
	v_max_f32_e32 v46, 0, v46
	v_add_f32_e32 v46, 0x358637bd, v46
	v_rsq_f32_e32 v46, v46
	v_sub_f32_e32 v49, v49, v85
	v_sub_f32_e32 v50, v79, v85
	v_sub_f32_e32 v79, v82, v85
	v_mul_f32_e32 v44, v45, v46
	v_fma_f32 v83, v11, v44, v7
	v_sub_f32_e32 v44, v48, v85
	v_mul_f32_e32 v44, v44, v46
	v_mul_f32_e32 v49, v49, v46
	v_mul_f32_e32 v50, v50, v46
	v_mul_f32_e32 v79, v79, v46
	v_fma_f32 v84, v0, v44, v2
	v_sub_f32_e32 v44, v78, v85
	v_fma_f32 v49, v8, v49, v4
	v_fma_f32 v50, v9, v50, v5
	v_fma_f32 v82, v10, v79, v6
	v_mul_f32_e32 v44, v44, v46
	v_cvt_pk_bf16_f32 v78, v35, v59
	v_cvt_pk_bf16_f32 v79, v68, v71
	v_cvt_pk_bf16_f32 v80, v74, v77
	v_cvt_pk_bf16_f32 v81, v86, v49
	v_add_u32_e32 v35, 0, v147
	v_fma_f32 v85, v1, v44, v3
	ds_write_b128 v35, v[78:81] offset:34816
	v_cvt_pk_bf16_f32 v78, v31, v55
	v_cvt_pk_bf16_f32 v79, v67, v70
	v_cvt_pk_bf16_f32 v80, v73, v76
	v_cvt_pk_bf16_f32 v81, v88, v50
	ds_write_b128 v35, v[78:81] offset:34832
	v_cvt_pk_bf16_f32 v48, v27, v51
	v_cvt_pk_bf16_f32 v49, v66, v69
	v_cvt_pk_bf16_f32 v50, v72, v75
	v_cvt_pk_bf16_f32 v51, v89, v82
	ds_write_b128 v35, v[48:51] offset:34848
	v_cvt_pk_bf16_f32 v44, v23, v47
	v_cvt_pk_bf16_f32 v45, v65, v62
	v_cvt_pk_bf16_f32 v46, v58, v54
	v_cvt_pk_bf16_f32 v47, v90, v83
	ds_write_b128 v35, v[44:47] offset:34864
	v_cvt_pk_bf16_f32 v44, v19, v43
	v_cvt_pk_bf16_f32 v45, v64, v61
	v_cvt_pk_bf16_f32 v46, v57, v53
	v_cvt_pk_bf16_f32 v47, v91, v84
	ds_write_b128 v35, v[44:47] offset:34880
	v_cvt_pk_bf16_f32 v44, v15, v39
	v_cvt_pk_bf16_f32 v45, v63, v60
	v_cvt_pk_bf16_f32 v46, v56, v52
	v_cvt_pk_bf16_f32 v47, v87, v85
	ds_write_b128 v35, v[44:47] offset:34896
	s_waitcnt vmcnt(7)
	v_lshlrev_b32_e32 v45, 16, v40
	v_lshlrev_b32_e32 v44, 16, v42
	v_and_b32_e32 v43, 0xffff0000, v40
	v_and_b32_e32 v42, 0xffff0000, v42
	v_lshlrev_b32_e32 v48, 16, v41
	v_and_b32_e32 v41, 0xffff0000, v41
	v_pk_add_f32 v[46:47], v[44:45], v[42:43]
	v_add_f32_e32 v15, v41, v48
	v_add_f32_e32 v15, v47, v15
	v_add_f32_e32 v15, v46, v15
	v_mov_b32_e32 v49, v41
	v_pk_mul_f32 v[46:47], v[48:49], v[48:49]
	v_pk_mul_f32 v[50:51], v[42:43], v[42:43]
	v_add_f32_e32 v19, v46, v47
	s_waitcnt lgkmcnt(0)
	s_nop 1
	v_add_f32_dpp v15, v15, v15 quad_perm:[1,0,3,2] row_mask:0xf bank_mask:0xf
	v_pk_fma_f32 v[50:51], v[44:45], v[44:45], v[50:51]
	v_and_b32_e32 v40, s0, v40
	v_add_f32_e32 v19, v51, v19
	v_add_f32_e32 v19, v50, v19
	s_waitcnt lgkmcnt(0)
	s_nop 1
	v_add_f32_dpp v15, v15, v15 quad_perm:[2,3,0,1] row_mask:0xf bank_mask:0xf
	s_waitcnt lgkmcnt(0)
	s_nop 1
	v_add_f32_dpp v15, v15, v15 row_half_mirror row_mask:0xf bank_mask:0xf
	s_waitcnt lgkmcnt(0)
	s_nop 1
	v_add_f32_dpp v15, v15, v15 row_mirror row_mask:0xf bank_mask:0xf
	ds_swizzle_b32 v23, v15 offset:swizzle(SWAP,16)
	s_waitcnt lgkmcnt(0)
	v_add_f32_e32 v47, v15, v23
	v_mov_b32_e32 v51, v47
	s_nop 1
	v_permlane32_swap_b32_e32 v47, v51
	s_waitcnt lgkmcnt(0)
	s_nop 1
	v_add_f32_dpp v15, v19, v19 quad_perm:[1,0,3,2] row_mask:0xf bank_mask:0xf
	s_waitcnt lgkmcnt(0)
	s_nop 1
	v_add_f32_dpp v15, v15, v15 quad_perm:[2,3,0,1] row_mask:0xf bank_mask:0xf
	s_waitcnt lgkmcnt(0)
	s_nop 1
	v_add_f32_dpp v15, v15, v15 row_half_mirror row_mask:0xf bank_mask:0xf
	s_waitcnt lgkmcnt(0)
	s_nop 1
	v_add_f32_dpp v15, v15, v15 row_mirror row_mask:0xf bank_mask:0xf
	ds_swizzle_b32 v19, v15 offset:swizzle(SWAP,16)
	s_waitcnt lgkmcnt(0)
	v_add_f32_e32 v46, v15, v19
	v_mov_b32_e32 v50, v46
	s_nop 1
	v_permlane32_swap_b32_e32 v46, v50
	v_pk_add_f32 v[46:47], v[46:47], v[50:51]
	s_nop 0
	v_pk_mul_f32 v[50:51], v[46:47], s[88:89] op_sel_hi:[1,0]
	v_pk_fma_f32 v[40:41], v[46:47], s[88:89], v[40:41] op_sel_hi:[1,0,1] neg_lo:[1,0,0] neg_hi:[1,0,0]
	v_fma_f32 v15, -v51, v51, v50
	v_max_f32_e32 v15, 0, v15
	v_add_f32_e32 v15, 0x358637bd, v15
	v_rsq_f32_e32 v15, v15
	v_sub_f32_e32 v19, v45, v51
	v_sub_f32_e32 v39, v42, v51
	s_waitcnt vmcnt(6)
	v_lshlrev_b32_e32 v42, 16, v38
	v_mul_f32_e32 v19, v19, v15
	v_fma_f32 v35, v8, v19, v4
	v_sub_f32_e32 v19, v43, v51
	v_mul_f32_e32 v19, v19, v15
	v_fma_f32 v31, v9, v19, v5
	v_sub_f32_e32 v19, v48, v51
	v_mul_f32_e32 v19, v19, v15
	v_fma_f32 v27, v10, v19, v6
	v_mul_f32_e32 v19, v41, v15
	v_fma_f32 v23, v11, v19, v7
	v_sub_f32_e32 v19, v44, v51
	v_lshlrev_b32_e32 v43, 16, v36
	v_and_b32_e32 v45, 0xffff0000, v36
	v_and_b32_e32 v44, 0xffff0000, v38
	v_lshlrev_b32_e32 v46, 16, v37
	v_and_b32_e32 v37, 0xffff0000, v37
	v_mul_f32_e32 v19, v19, v15
	v_mul_f32_e32 v15, v39, v15
	v_pk_add_f32 v[38:39], v[42:43], v[44:45]
	v_add_f32_e32 v40, v37, v46
	v_mov_b32_e32 v47, v37
	v_add_f32_e32 v39, v39, v40
	v_add_f32_e32 v48, v38, v39
	v_pk_mul_f32 v[38:39], v[46:47], v[46:47]
	v_pk_mul_f32 v[40:41], v[44:45], v[44:45]
	v_add_f32_e32 v38, v38, v39
	v_pk_fma_f32 v[40:41], v[42:43], v[42:43], v[40:41]
	v_and_b32_e32 v36, s0, v36
	v_add_f32_e32 v38, v41, v38
	v_add_f32_e32 v38, v40, v38
	s_waitcnt lgkmcnt(0)
	s_nop 1
	v_add_f32_dpp v39, v48, v48 quad_perm:[1,0,3,2] row_mask:0xf bank_mask:0xf
	v_fma_f32 v19, v0, v19, v2
	v_fma_f32 v15, v1, v15, v3
	s_waitcnt lgkmcnt(0)
	s_nop 1
	v_add_f32_dpp v39, v39, v39 quad_perm:[2,3,0,1] row_mask:0xf bank_mask:0xf
	s_waitcnt lgkmcnt(0)
	s_nop 1
	v_add_f32_dpp v39, v39, v39 row_half_mirror row_mask:0xf bank_mask:0xf
	s_waitcnt lgkmcnt(0)
	s_nop 1
	v_add_f32_dpp v39, v39, v39 row_mirror row_mask:0xf bank_mask:0xf
	ds_swizzle_b32 v40, v39 offset:swizzle(SWAP,16)
	s_waitcnt lgkmcnt(0)
	v_add_f32_e32 v39, v39, v40
	v_mov_b32_e32 v41, v39
	s_nop 1
	v_permlane32_swap_b32_e32 v39, v41
	s_waitcnt lgkmcnt(0)
	s_nop 1
	v_add_f32_dpp v38, v38, v38 quad_perm:[1,0,3,2] row_mask:0xf bank_mask:0xf
	s_waitcnt lgkmcnt(0)
	s_nop 1
	v_add_f32_dpp v38, v38, v38 quad_perm:[2,3,0,1] row_mask:0xf bank_mask:0xf
	s_waitcnt lgkmcnt(0)
	s_nop 1
	v_add_f32_dpp v38, v38, v38 row_half_mirror row_mask:0xf bank_mask:0xf
	s_waitcnt lgkmcnt(0)
	s_nop 1
	v_add_f32_dpp v38, v38, v38 row_mirror row_mask:0xf bank_mask:0xf
	ds_swizzle_b32 v40, v38 offset:swizzle(SWAP,16)
	s_waitcnt lgkmcnt(0)
	v_add_f32_e32 v38, v38, v40
	v_mov_b32_e32 v40, v38
	s_nop 1
	v_permlane32_swap_b32_e32 v38, v40
	v_pk_add_f32 v[48:49], v[38:39], v[40:41]
	s_nop 0
	v_pk_mul_f32 v[50:51], v[48:49], s[88:89] op_sel_hi:[1,0]
	v_pk_fma_f32 v[36:37], v[48:49], s[88:89], v[36:37] op_sel_hi:[1,0,1] neg_lo:[1,0,0] neg_hi:[1,0,0]
	v_fma_f32 v38, -v51, v51, v50
	v_max_f32_e32 v38, 0, v38
	v_add_f32_e32 v38, 0x358637bd, v38
	v_rsq_f32_e32 v47, v38
	v_sub_f32_e32 v38, v43, v51
	s_waitcnt vmcnt(5)
	v_and_b32_e32 v49, 0xffff0000, v32
	v_and_b32_e32 v48, 0xffff0000, v34
	v_mul_f32_e32 v38, v38, v47
	v_fma_f32 v41, v8, v38, v4
	v_sub_f32_e32 v38, v45, v51
	v_mul_f32_e32 v38, v38, v47
	v_fma_f32 v40, v9, v38, v5
	v_sub_f32_e32 v38, v46, v51
	v_mul_f32_e32 v38, v38, v47
	v_mul_f32_e32 v36, v37, v47
	v_fma_f32 v39, v10, v38, v6
	v_fma_f32 v38, v11, v36, v7
	v_sub_f32_e32 v36, v42, v51
	v_mul_f32_e32 v36, v36, v47
	v_fma_f32 v37, v0, v36, v2
	v_sub_f32_e32 v36, v44, v51
	v_mul_f32_e32 v36, v36, v47
	v_lshlrev_b32_e32 v47, 16, v32
	v_lshlrev_b32_e32 v46, 16, v34
	v_lshlrev_b32_e32 v50, 16, v33
	v_and_b32_e32 v33, 0xffff0000, v33
	v_pk_add_f32 v[42:43], v[46:47], v[48:49]
	v_add_f32_e32 v34, v33, v50
	v_mov_b32_e32 v51, v33
	v_add_f32_e32 v34, v43, v34
	v_add_f32_e32 v34, v42, v34
	v_pk_mul_f32 v[42:43], v[50:51], v[50:51]
	v_pk_mul_f32 v[44:45], v[48:49], v[48:49]
	v_add_f32_e32 v42, v42, v43
	v_pk_fma_f32 v[44:45], v[46:47], v[46:47], v[44:45]
	v_and_b32_e32 v32, s0, v32
	v_add_f32_e32 v42, v45, v42
	v_add_f32_e32 v42, v44, v42
	s_waitcnt lgkmcnt(0)
	s_nop 1
	v_add_f32_dpp v34, v34, v34 quad_perm:[1,0,3,2] row_mask:0xf bank_mask:0xf
	v_fma_f32 v36, v1, v36, v3
	s_waitcnt lgkmcnt(0)
	s_nop 1
	v_add_f32_dpp v34, v34, v34 quad_perm:[2,3,0,1] row_mask:0xf bank_mask:0xf
	s_waitcnt lgkmcnt(0)
	s_nop 1
	v_add_f32_dpp v34, v34, v34 row_half_mirror row_mask:0xf bank_mask:0xf
	s_waitcnt lgkmcnt(0)
	s_nop 1
	v_add_f32_dpp v34, v34, v34 row_mirror row_mask:0xf bank_mask:0xf
	ds_swizzle_b32 v43, v34 offset:swizzle(SWAP,16)
	s_waitcnt lgkmcnt(0)
	v_add_f32_e32 v43, v34, v43
	v_mov_b32_e32 v45, v43
	s_nop 1
	v_permlane32_swap_b32_e32 v43, v45
	s_waitcnt lgkmcnt(0)
	s_nop 1
	v_add_f32_dpp v34, v42, v42 quad_perm:[1,0,3,2] row_mask:0xf bank_mask:0xf
	s_waitcnt lgkmcnt(0)
	s_nop 1
	v_add_f32_dpp v34, v34, v34 quad_perm:[2,3,0,1] row_mask:0xf bank_mask:0xf
	s_waitcnt lgkmcnt(0)
	s_nop 1
	v_add_f32_dpp v34, v34, v34 row_half_mirror row_mask:0xf bank_mask:0xf
	s_waitcnt lgkmcnt(0)
	s_nop 1
	v_add_f32_dpp v34, v34, v34 row_mirror row_mask:0xf bank_mask:0xf
	ds_swizzle_b32 v42, v34 offset:swizzle(SWAP,16)
	s_waitcnt lgkmcnt(0)
	v_add_f32_e32 v42, v34, v42
	v_mov_b32_e32 v44, v42
	s_nop 1
	v_permlane32_swap_b32_e32 v42, v44
	v_pk_add_f32 v[52:53], v[42:43], v[44:45]
	s_nop 0
	v_pk_mul_f32 v[44:45], v[52:53], s[88:89] op_sel_hi:[1,0]
	v_pk_fma_f32 v[32:33], v[52:53], s[88:89], v[32:33] op_sel_hi:[1,0,1] neg_lo:[1,0,0] neg_hi:[1,0,0]
	v_fma_f32 v34, -v45, v45, v44
	v_max_f32_e32 v34, 0, v34
	v_add_f32_e32 v34, 0x358637bd, v34
	v_rsq_f32_e32 v51, v34
	v_sub_f32_e32 v34, v47, v45
	s_waitcnt vmcnt(4)
	v_lshlrev_b32_e32 v52, 16, v29
	v_and_b32_e32 v29, 0xffff0000, v29
	v_mul_f32_e32 v34, v34, v51
	v_fma_f32 v44, v8, v34, v4
	v_sub_f32_e32 v34, v49, v45
	v_mul_f32_e32 v34, v34, v51
	v_fma_f32 v43, v9, v34, v5
	v_sub_f32_e32 v34, v50, v45
	v_mul_f32_e32 v34, v34, v51
	v_mul_f32_e32 v32, v33, v51
	v_fma_f32 v42, v10, v34, v6
	v_fma_f32 v34, v11, v32, v7
	v_sub_f32_e32 v32, v46, v45
	v_mul_f32_e32 v32, v32, v51
	v_fma_f32 v33, v0, v32, v2
	v_sub_f32_e32 v32, v48, v45
	v_mul_f32_e32 v32, v32, v51
	v_lshlrev_b32_e32 v49, 16, v28
	v_lshlrev_b32_e32 v48, 16, v30
	v_and_b32_e32 v51, 0xffff0000, v28
	v_and_b32_e32 v50, 0xffff0000, v30
	v_pk_add_f32 v[46:47], v[48:49], v[50:51]
	v_add_f32_e32 v30, v29, v52
	v_mov_b32_e32 v53, v29
	v_add_f32_e32 v30, v47, v30
	v_add_f32_e32 v30, v46, v30
	v_pk_mul_f32 v[46:47], v[52:53], v[52:53]
	v_pk_mul_f32 v[54:55], v[50:51], v[50:51]
	v_add_f32_e32 v45, v46, v47
	v_pk_fma_f32 v[54:55], v[48:49], v[48:49], v[54:55]
	v_and_b32_e32 v28, s0, v28
	v_add_f32_e32 v45, v55, v45
	v_add_f32_e32 v45, v54, v45
	s_waitcnt lgkmcnt(0)
	s_nop 1
	v_add_f32_dpp v30, v30, v30 quad_perm:[1,0,3,2] row_mask:0xf bank_mask:0xf
	v_fma_f32 v32, v1, v32, v3
	s_waitcnt lgkmcnt(0)
	s_nop 1
	v_add_f32_dpp v30, v30, v30 quad_perm:[2,3,0,1] row_mask:0xf bank_mask:0xf
	s_waitcnt lgkmcnt(0)
	s_nop 1
	v_add_f32_dpp v30, v30, v30 row_half_mirror row_mask:0xf bank_mask:0xf
	s_waitcnt lgkmcnt(0)
	s_nop 1
	v_add_f32_dpp v30, v30, v30 row_mirror row_mask:0xf bank_mask:0xf
	ds_swizzle_b32 v46, v30 offset:swizzle(SWAP,16)
	s_waitcnt lgkmcnt(0)
	v_add_f32_e32 v47, v30, v46
	v_mov_b32_e32 v55, v47
	s_nop 1
	v_permlane32_swap_b32_e32 v47, v55
	s_waitcnt lgkmcnt(0)
	s_nop 1
	v_add_f32_dpp v30, v45, v45 quad_perm:[1,0,3,2] row_mask:0xf bank_mask:0xf
	s_waitcnt lgkmcnt(0)
	s_nop 1
	v_add_f32_dpp v30, v30, v30 quad_perm:[2,3,0,1] row_mask:0xf bank_mask:0xf
	s_waitcnt lgkmcnt(0)
	s_nop 1
	v_add_f32_dpp v30, v30, v30 row_half_mirror row_mask:0xf bank_mask:0xf
	s_waitcnt lgkmcnt(0)
	s_nop 1
	v_add_f32_dpp v30, v30, v30 row_mirror row_mask:0xf bank_mask:0xf
	ds_swizzle_b32 v45, v30 offset:swizzle(SWAP,16)
	s_waitcnt lgkmcnt(0)
	v_add_f32_e32 v46, v30, v45
	v_mov_b32_e32 v54, v46
	s_nop 1
	v_permlane32_swap_b32_e32 v46, v54
	v_pk_add_f32 v[54:55], v[46:47], v[54:55]
	s_nop 0
	v_pk_mul_f32 v[56:57], v[54:55], s[88:89] op_sel_hi:[1,0]
	v_pk_fma_f32 v[28:29], v[54:55], s[88:89], v[28:29] op_sel_hi:[1,0,1] neg_lo:[1,0,0] neg_hi:[1,0,0]
	v_fma_f32 v30, -v57, v57, v56
	v_max_f32_e32 v30, 0, v30
	v_add_f32_e32 v30, 0x358637bd, v30
	v_rsq_f32_e32 v53, v30
	v_sub_f32_e32 v30, v49, v57
	s_waitcnt vmcnt(3)
	v_and_b32_e32 v55, 0xffff0000, v24
	v_and_b32_e32 v54, 0xffff0000, v26
	v_mul_f32_e32 v30, v30, v53
	v_fma_f32 v47, v8, v30, v4
	v_sub_f32_e32 v30, v51, v57
	v_mul_f32_e32 v30, v30, v53
	v_fma_f32 v46, v9, v30, v5
	v_sub_f32_e32 v30, v52, v57
	v_mul_f32_e32 v30, v30, v53
	v_mul_f32_e32 v28, v29, v53
	v_fma_f32 v45, v10, v30, v6
	v_fma_f32 v30, v11, v28, v7
	v_sub_f32_e32 v28, v48, v57
	v_mul_f32_e32 v28, v28, v53
	v_fma_f32 v29, v0, v28, v2
	v_sub_f32_e32 v28, v50, v57
	v_mul_f32_e32 v28, v28, v53
	v_lshlrev_b32_e32 v53, 16, v24
	v_lshlrev_b32_e32 v52, 16, v26
	v_lshlrev_b32_e32 v56, 16, v25
	v_and_b32_e32 v25, 0xffff0000, v25
	v_pk_add_f32 v[48:49], v[52:53], v[54:55]
	v_add_f32_e32 v26, v25, v56
	v_mov_b32_e32 v57, v25
	v_add_f32_e32 v26, v49, v26
	v_add_f32_e32 v26, v48, v26
	v_pk_mul_f32 v[48:49], v[56:57], v[56:57]
	v_pk_mul_f32 v[50:51], v[54:55], v[54:55]
	v_add_f32_e32 v48, v48, v49
	v_pk_fma_f32 v[50:51], v[52:53], v[52:53], v[50:51]
	v_and_b32_e32 v24, s0, v24
	v_add_f32_e32 v48, v51, v48
	v_add_f32_e32 v48, v50, v48
	s_waitcnt lgkmcnt(0)
	s_nop 1
	v_add_f32_dpp v26, v26, v26 quad_perm:[1,0,3,2] row_mask:0xf bank_mask:0xf
	v_fma_f32 v28, v1, v28, v3
	s_waitcnt lgkmcnt(0)
	s_nop 1
	v_add_f32_dpp v26, v26, v26 quad_perm:[2,3,0,1] row_mask:0xf bank_mask:0xf
	s_waitcnt lgkmcnt(0)
	s_nop 1
	v_add_f32_dpp v26, v26, v26 row_half_mirror row_mask:0xf bank_mask:0xf
	s_waitcnt lgkmcnt(0)
	s_nop 1
	v_add_f32_dpp v26, v26, v26 row_mirror row_mask:0xf bank_mask:0xf
	ds_swizzle_b32 v49, v26 offset:swizzle(SWAP,16)
	s_waitcnt lgkmcnt(0)
	v_add_f32_e32 v49, v26, v49
	v_mov_b32_e32 v51, v49
	s_nop 1
	v_permlane32_swap_b32_e32 v49, v51
	s_waitcnt lgkmcnt(0)
	s_nop 1
	v_add_f32_dpp v26, v48, v48 quad_perm:[1,0,3,2] row_mask:0xf bank_mask:0xf
	s_waitcnt lgkmcnt(0)
	s_nop 1
	v_add_f32_dpp v26, v26, v26 quad_perm:[2,3,0,1] row_mask:0xf bank_mask:0xf
	s_waitcnt lgkmcnt(0)
	s_nop 1
	v_add_f32_dpp v26, v26, v26 row_half_mirror row_mask:0xf bank_mask:0xf
	s_waitcnt lgkmcnt(0)
	s_nop 1
	v_add_f32_dpp v26, v26, v26 row_mirror row_mask:0xf bank_mask:0xf
	ds_swizzle_b32 v48, v26 offset:swizzle(SWAP,16)
	s_waitcnt lgkmcnt(0)
	v_add_f32_e32 v48, v26, v48
	v_mov_b32_e32 v50, v48
	s_nop 1
	v_permlane32_swap_b32_e32 v48, v50
	v_pk_add_f32 v[58:59], v[48:49], v[50:51]
	s_nop 0
	v_pk_mul_f32 v[50:51], v[58:59], s[88:89] op_sel_hi:[1,0]
	v_pk_fma_f32 v[24:25], v[58:59], s[88:89], v[24:25] op_sel_hi:[1,0,1] neg_lo:[1,0,0] neg_hi:[1,0,0]
	v_fma_f32 v26, -v51, v51, v50
	v_max_f32_e32 v26, 0, v26
	v_add_f32_e32 v26, 0x358637bd, v26
	v_rsq_f32_e32 v57, v26
	v_sub_f32_e32 v26, v53, v51
	s_waitcnt vmcnt(2)
	v_lshlrev_b32_e32 v58, 16, v21
	v_and_b32_e32 v21, 0xffff0000, v21
	v_mul_f32_e32 v26, v26, v57
	v_fma_f32 v50, v8, v26, v4
	v_sub_f32_e32 v26, v55, v51
	v_mul_f32_e32 v26, v26, v57
	v_fma_f32 v49, v9, v26, v5
	v_sub_f32_e32 v26, v56, v51
	v_mul_f32_e32 v26, v26, v57
	v_mul_f32_e32 v24, v25, v57
	v_fma_f32 v48, v10, v26, v6
	v_fma_f32 v26, v11, v24, v7
	v_sub_f32_e32 v24, v52, v51
	v_mul_f32_e32 v24, v24, v57
	v_fma_f32 v25, v0, v24, v2
	v_sub_f32_e32 v24, v54, v51
	v_mul_f32_e32 v24, v24, v57
	v_lshlrev_b32_e32 v55, 16, v20
	v_lshlrev_b32_e32 v54, 16, v22
	v_and_b32_e32 v57, 0xffff0000, v20
	v_and_b32_e32 v56, 0xffff0000, v22
	v_pk_add_f32 v[52:53], v[54:55], v[56:57]
	v_add_f32_e32 v22, v21, v58
	v_mov_b32_e32 v59, v21
	v_add_f32_e32 v22, v53, v22
	v_add_f32_e32 v22, v52, v22
	v_pk_mul_f32 v[52:53], v[58:59], v[58:59]
	v_pk_mul_f32 v[60:61], v[56:57], v[56:57]
	v_add_f32_e32 v51, v52, v53
	v_pk_fma_f32 v[60:61], v[54:55], v[54:55], v[60:61]
	v_and_b32_e32 v20, s0, v20
	v_add_f32_e32 v51, v61, v51
	v_add_f32_e32 v51, v60, v51
	s_waitcnt lgkmcnt(0)
	s_nop 1
	v_add_f32_dpp v22, v22, v22 quad_perm:[1,0,3,2] row_mask:0xf bank_mask:0xf
	v_fma_f32 v24, v1, v24, v3
	s_waitcnt lgkmcnt(0)
	s_nop 1
	v_add_f32_dpp v22, v22, v22 quad_perm:[2,3,0,1] row_mask:0xf bank_mask:0xf
	s_waitcnt lgkmcnt(0)
	s_nop 1
	v_add_f32_dpp v22, v22, v22 row_half_mirror row_mask:0xf bank_mask:0xf
	s_waitcnt lgkmcnt(0)
	s_nop 1
	v_add_f32_dpp v22, v22, v22 row_mirror row_mask:0xf bank_mask:0xf
	ds_swizzle_b32 v52, v22 offset:swizzle(SWAP,16)
	s_waitcnt lgkmcnt(0)
	v_add_f32_e32 v53, v22, v52
	v_mov_b32_e32 v61, v53
	s_nop 1
	v_permlane32_swap_b32_e32 v53, v61
	s_waitcnt lgkmcnt(0)
	s_nop 1
	v_add_f32_dpp v22, v51, v51 quad_perm:[1,0,3,2] row_mask:0xf bank_mask:0xf
	s_waitcnt lgkmcnt(0)
	s_nop 1
	v_add_f32_dpp v22, v22, v22 quad_perm:[2,3,0,1] row_mask:0xf bank_mask:0xf
	s_waitcnt lgkmcnt(0)
	s_nop 1
	v_add_f32_dpp v22, v22, v22 row_half_mirror row_mask:0xf bank_mask:0xf
	s_waitcnt lgkmcnt(0)
	s_nop 1
	v_add_f32_dpp v22, v22, v22 row_mirror row_mask:0xf bank_mask:0xf
	ds_swizzle_b32 v51, v22 offset:swizzle(SWAP,16)
	s_waitcnt lgkmcnt(0)
	v_add_f32_e32 v52, v22, v51
	v_mov_b32_e32 v60, v52
	s_nop 1
	v_permlane32_swap_b32_e32 v52, v60
	v_pk_add_f32 v[60:61], v[52:53], v[60:61]
	s_nop 0
	v_pk_mul_f32 v[62:63], v[60:61], s[88:89] op_sel_hi:[1,0]
	v_pk_fma_f32 v[20:21], v[60:61], s[88:89], v[20:21] op_sel_hi:[1,0,1] neg_lo:[1,0,0] neg_hi:[1,0,0]
	v_fma_f32 v22, -v63, v63, v62
	v_max_f32_e32 v22, 0, v22
	v_add_f32_e32 v22, 0x358637bd, v22
	v_rsq_f32_e32 v59, v22
	v_sub_f32_e32 v22, v55, v63
	s_waitcnt vmcnt(1)
	v_lshlrev_b32_e32 v55, 16, v16
	v_lshlrev_b32_e32 v60, 16, v17
	v_mul_f32_e32 v22, v22, v59
	v_fma_f32 v53, v8, v22, v4
	v_sub_f32_e32 v22, v57, v63
	v_mul_f32_e32 v22, v22, v59
	v_fma_f32 v52, v9, v22, v5
	v_sub_f32_e32 v22, v58, v63
	v_mul_f32_e32 v22, v22, v59
	v_mul_f32_e32 v20, v21, v59
	v_fma_f32 v51, v10, v22, v6
	v_fma_f32 v22, v11, v20, v7
	v_sub_f32_e32 v20, v54, v63
	v_mul_f32_e32 v20, v20, v59
	v_fma_f32 v21, v0, v20, v2
	v_sub_f32_e32 v20, v56, v63
	v_lshlrev_b32_e32 v54, 16, v18
	v_and_b32_e32 v57, 0xffff0000, v16
	v_and_b32_e32 v56, 0xffff0000, v18
	v_and_b32_e32 v17, 0xffff0000, v17
	v_mul_f32_e32 v20, v20, v59
	v_pk_add_f32 v[58:59], v[54:55], v[56:57]
	v_add_f32_e32 v18, v17, v60
	v_mov_b32_e32 v61, v17
	v_add_f32_e32 v18, v59, v18
	v_add_f32_e32 v18, v58, v18
	v_pk_mul_f32 v[58:59], v[60:61], v[60:61]
	v_pk_mul_f32 v[62:63], v[56:57], v[56:57]
	v_add_f32_e32 v58, v58, v59
	v_pk_fma_f32 v[62:63], v[54:55], v[54:55], v[62:63]
	v_and_b32_e32 v16, s0, v16
	v_add_f32_e32 v58, v63, v58
	v_add_f32_e32 v58, v62, v58
	s_waitcnt lgkmcnt(0)
	s_nop 1
	v_add_f32_dpp v18, v18, v18 quad_perm:[1,0,3,2] row_mask:0xf bank_mask:0xf
	v_fma_f32 v20, v1, v20, v3
	s_waitcnt lgkmcnt(0)
	s_nop 1
	v_add_f32_dpp v18, v18, v18 quad_perm:[2,3,0,1] row_mask:0xf bank_mask:0xf
	s_waitcnt lgkmcnt(0)
	s_nop 1
	v_add_f32_dpp v18, v18, v18 row_half_mirror row_mask:0xf bank_mask:0xf
	s_waitcnt lgkmcnt(0)
	s_nop 1
	v_add_f32_dpp v18, v18, v18 row_mirror row_mask:0xf bank_mask:0xf
	ds_swizzle_b32 v59, v18 offset:swizzle(SWAP,16)
	s_waitcnt lgkmcnt(0)
	v_add_f32_e32 v59, v18, v59
	v_mov_b32_e32 v63, v59
	s_nop 1
	v_permlane32_swap_b32_e32 v59, v63
	s_waitcnt lgkmcnt(0)
	s_nop 1
	v_add_f32_dpp v18, v58, v58 quad_perm:[1,0,3,2] row_mask:0xf bank_mask:0xf
	s_waitcnt lgkmcnt(0)
	s_nop 1
	v_add_f32_dpp v18, v18, v18 quad_perm:[2,3,0,1] row_mask:0xf bank_mask:0xf
	s_waitcnt lgkmcnt(0)
	s_nop 1
	v_add_f32_dpp v18, v18, v18 row_half_mirror row_mask:0xf bank_mask:0xf
	s_waitcnt lgkmcnt(0)
	s_nop 1
	v_add_f32_dpp v18, v18, v18 row_mirror row_mask:0xf bank_mask:0xf
	ds_swizzle_b32 v58, v18 offset:swizzle(SWAP,16)
	s_waitcnt lgkmcnt(0)
	v_add_f32_e32 v58, v18, v58
	v_mov_b32_e32 v62, v58
	s_nop 1
	v_permlane32_swap_b32_e32 v58, v62
	v_pk_add_f32 v[58:59], v[58:59], v[62:63]
	s_nop 0
	v_pk_mul_f32 v[62:63], v[58:59], s[88:89] op_sel_hi:[1,0]
	v_pk_fma_f32 v[16:17], v[58:59], s[88:89], v[16:17] op_sel_hi:[1,0,1] neg_lo:[1,0,0] neg_hi:[1,0,0]
	v_fma_f32 v18, -v63, v63, v62
	v_max_f32_e32 v18, 0, v18
	v_add_f32_e32 v18, 0x358637bd, v18
	v_rsq_f32_e32 v18, v18
	v_sub_f32_e32 v55, v55, v63
	s_waitcnt vmcnt(0)
	v_lshlrev_b32_e32 v58, 16, v13
	v_and_b32_e32 v13, 0xffff0000, v13
	v_mul_f32_e32 v55, v55, v18
	v_mul_f32_e32 v16, v17, v18
	v_fma_f32 v62, v8, v55, v4
	v_sub_f32_e32 v55, v57, v63
	v_fma_f32 v66, v11, v16, v7
	v_sub_f32_e32 v16, v54, v63
	v_mul_f32_e32 v55, v55, v18
	v_mul_f32_e32 v16, v16, v18
	v_fma_f32 v64, v9, v55, v5
	v_sub_f32_e32 v55, v60, v63
	v_fma_f32 v67, v0, v16, v2
	v_sub_f32_e32 v16, v56, v63
	v_mul_f32_e32 v55, v55, v18
	v_mul_f32_e32 v16, v16, v18
	v_fma_f32 v65, v10, v55, v6
	v_fma_f32 v18, v1, v16, v3
	v_lshlrev_b32_e32 v17, 16, v12
	v_lshlrev_b32_e32 v16, 16, v14
	v_and_b32_e32 v55, 0xffff0000, v12
	v_and_b32_e32 v54, 0xffff0000, v14
	v_pk_add_f32 v[56:57], v[16:17], v[54:55]
	v_add_f32_e32 v14, v13, v58
	v_mov_b32_e32 v59, v13
	v_add_f32_e32 v14, v57, v14
	v_add_f32_e32 v14, v56, v14
	v_pk_mul_f32 v[56:57], v[58:59], v[58:59]
	v_pk_mul_f32 v[60:61], v[54:55], v[54:55]
	v_add_f32_e32 v56, v56, v57
	v_pk_fma_f32 v[60:61], v[16:17], v[16:17], v[60:61]
	v_and_b32_e32 v12, s0, v12
	v_add_f32_e32 v56, v61, v56
	v_add_f32_e32 v56, v60, v56
	s_waitcnt lgkmcnt(0)
	s_nop 1
	v_add_f32_dpp v14, v14, v14 quad_perm:[1,0,3,2] row_mask:0xf bank_mask:0xf
	s_waitcnt lgkmcnt(0)
	s_nop 1
	v_add_f32_dpp v14, v14, v14 quad_perm:[2,3,0,1] row_mask:0xf bank_mask:0xf
	s_waitcnt lgkmcnt(0)
	s_nop 1
	v_add_f32_dpp v14, v14, v14 row_half_mirror row_mask:0xf bank_mask:0xf
	s_waitcnt lgkmcnt(0)
	s_nop 1
	v_add_f32_dpp v14, v14, v14 row_mirror row_mask:0xf bank_mask:0xf
	ds_swizzle_b32 v57, v14 offset:swizzle(SWAP,16)
	s_waitcnt lgkmcnt(0)
	v_add_f32_e32 v57, v14, v57
	v_mov_b32_e32 v61, v57
	s_nop 1
	v_permlane32_swap_b32_e32 v57, v61
	s_waitcnt lgkmcnt(0)
	s_nop 1
	v_add_f32_dpp v14, v56, v56 quad_perm:[1,0,3,2] row_mask:0xf bank_mask:0xf
	s_waitcnt lgkmcnt(0)
	s_nop 1
	v_add_f32_dpp v14, v14, v14 quad_perm:[2,3,0,1] row_mask:0xf bank_mask:0xf
	s_waitcnt lgkmcnt(0)
	s_nop 1
	v_add_f32_dpp v14, v14, v14 row_half_mirror row_mask:0xf bank_mask:0xf
	s_waitcnt lgkmcnt(0)
	s_nop 1
	v_add_f32_dpp v14, v14, v14 row_mirror row_mask:0xf bank_mask:0xf
	ds_swizzle_b32 v56, v14 offset:swizzle(SWAP,16)
	s_waitcnt lgkmcnt(0)
	v_add_f32_e32 v56, v14, v56
	v_mov_b32_e32 v60, v56
	s_nop 1
	v_permlane32_swap_b32_e32 v56, v60
	v_pk_add_f32 v[56:57], v[56:57], v[60:61]
	s_nop 0
	v_pk_mul_f32 v[60:61], v[56:57], s[88:89] op_sel_hi:[1,0]
	s_nop 0
	v_fma_f32 v14, -v61, v61, v60
	v_max_f32_e32 v14, 0, v14
	v_add_f32_e32 v14, 0x358637bd, v14
	v_rsq_f32_e32 v14, v14
	v_sub_f32_e32 v17, v17, v61
	v_mul_f32_e32 v17, v17, v14
	v_fma_f32 v4, v8, v17, v4
	v_sub_f32_e32 v8, v55, v61
	v_mul_f32_e32 v8, v8, v14
	v_fmac_f32_e32 v5, v9, v8
	v_sub_f32_e32 v8, v58, v61
	v_mul_f32_e32 v8, v8, v14
	v_fma_f32 v6, v10, v8, v6
	v_pk_fma_f32 v[8:9], v[56:57], s[88:89], v[12:13] op_sel_hi:[1,0,1] neg_lo:[1,0,0] neg_hi:[1,0,0]
	s_nop 0
	v_mul_f32_e32 v8, v9, v14
	v_fmac_f32_e32 v7, v11, v8
	v_sub_f32_e32 v8, v16, v61
	v_mul_f32_e32 v8, v8, v14
	v_fma_f32 v0, v0, v8, v2
	v_cvt_pk_bf16_f32 v8, v35, v41
	v_cvt_pk_bf16_f32 v9, v44, v47
	v_cvt_pk_bf16_f32 v10, v50, v53
	v_cvt_pk_bf16_f32 v11, v62, v4
	v_sub_f32_e32 v2, v54, v61
	ds_write_b128 v251, v[8:11] offset:34816
	v_cvt_pk_bf16_f32 v8, v31, v40
	v_cvt_pk_bf16_f32 v9, v43, v46
	v_cvt_pk_bf16_f32 v10, v49, v52
	v_cvt_pk_bf16_f32 v11, v64, v5
	v_mul_f32_e32 v2, v2, v14
	ds_write_b128 v251, v[8:11] offset:34832
	v_cvt_pk_bf16_f32 v8, v27, v39
	v_cvt_pk_bf16_f32 v9, v42, v45
	v_cvt_pk_bf16_f32 v10, v48, v51
	v_cvt_pk_bf16_f32 v11, v65, v6
	ds_write_b128 v251, v[8:11] offset:34848
	v_cvt_pk_bf16_f32 v4, v23, v38
	v_cvt_pk_bf16_f32 v5, v34, v30
	v_cvt_pk_bf16_f32 v6, v26, v22
	v_cvt_pk_bf16_f32 v7, v66, v7
	v_fmac_f32_e32 v3, v1, v2
	ds_write_b128 v251, v[4:7] offset:34864
	v_cvt_pk_bf16_f32 v4, v19, v37
	v_cvt_pk_bf16_f32 v5, v33, v29
	v_cvt_pk_bf16_f32 v6, v25, v21
	v_cvt_pk_bf16_f32 v7, v67, v0
	ds_write_b128 v251, v[4:7] offset:34880
	v_cvt_pk_bf16_f32 v0, v15, v36
	v_cvt_pk_bf16_f32 v1, v32, v28
	v_cvt_pk_bf16_f32 v2, v24, v20
	v_cvt_pk_bf16_f32 v3, v18, v3
	ds_write_b128 v251, v[0:3] offset:34896
	v_add_u32_e32 v2, s16, v171
	v_lshl_add_u64 v[0:1], v[150:151], 0, s[70:71]
	v_or_b32_e32 v3, 16, v2
	v_mad_i64_i32 v[224:225], s[16:17], v2, s53, v[0:1]
	v_mad_i64_i32 v[210:211], s[16:17], v3, s53, v[0:1]
	v_or_b32_e32 v3, 32, v2
	v_or_b32_e32 v2, 48, v2
	v_mad_i64_i32 v[196:197], s[16:17], v3, s53, v[0:1]
	v_mad_i64_i32 v[176:177], s[16:17], v2, s53, v[0:1]
	s_waitcnt lgkmcnt(0)
	s_barrier
	global_load_dwordx2 v[236:237], v[224:225], off
	global_load_dwordx2 v[234:235], v[224:225], off offset:32
	global_load_dwordx2 v[232:233], v[224:225], off offset:64
	global_load_dwordx2 v[230:231], v[224:225], off offset:96
	global_load_dwordx2 v[228:229], v[224:225], off offset:128
	global_load_dwordx2 v[226:227], v[224:225], off offset:160
	global_load_dwordx2 v[222:223], v[210:211], off
	global_load_dwordx2 v[220:221], v[210:211], off offset:32
	global_load_dwordx2 v[218:219], v[210:211], off offset:64
	global_load_dwordx2 v[216:217], v[210:211], off offset:96
	global_load_dwordx2 v[214:215], v[210:211], off offset:128
	global_load_dwordx2 v[212:213], v[210:211], off offset:160
	global_load_dwordx2 v[208:209], v[196:197], off
	global_load_dwordx2 v[206:207], v[196:197], off offset:32
	global_load_dwordx2 v[204:205], v[196:197], off offset:64
	global_load_dwordx2 v[202:203], v[196:197], off offset:96
	global_load_dwordx2 v[200:201], v[196:197], off offset:128
	global_load_dwordx2 v[198:199], v[196:197], off offset:160
	global_load_dwordx2 v[194:195], v[176:177], off
	global_load_dwordx2 v[192:193], v[176:177], off offset:32
	global_load_dwordx2 v[190:191], v[176:177], off offset:64
	global_load_dwordx2 v[182:183], v[176:177], off offset:96
	global_load_dwordx2 v[180:181], v[176:177], off offset:128
	global_load_dwordx2 v[178:179], v[176:177], off offset:160
	ds_read_b128 v[84:87], v140 offset:34816
	ds_read_b128 v[88:91], v140 offset:35072
	ds_read_b128 v[92:95], v140 offset:35328
	ds_read_b128 v[80:83], v140 offset:35584
	ds_read_b128 v[72:75], v140 offset:35840
	ds_read_b128 v[76:79], v140 offset:36096
	ds_read_b128 v[0:3], v239
	ds_read_b128 v[32:35], v239 offset:4352
	ds_read_b128 v[52:55], v239 offset:8704
	ds_read_b128 v[116:119], v239 offset:13056
	ds_read_b128 v[120:123], v140 offset:59392
	ds_read_b128 v[124:127], v140 offset:59648
	ds_read_b128 v[128:131], v140 offset:59904
	ds_read_b128 v[132:135], v140 offset:60160
	ds_read_b128 v[136:139], v140 offset:60416
	ds_read_b128 v[140:143], v140 offset:60672
	s_waitcnt lgkmcnt(9)
	v_mfma_f32_16x16x32_bf16 v[20:23], v[84:87], v[0:3], 0
	v_readlane_b32 s16, v254, 6
	v_readlane_b32 s17, v254, 7
	s_andn2_b64 vcc, exec, s[16:17]
	v_mfma_f32_16x16x32_bf16 v[16:19], v[88:91], v[0:3], 0
	v_mfma_f32_16x16x32_bf16 v[12:15], v[92:95], v[0:3], 0
	v_mfma_f32_16x16x32_bf16 v[8:11], v[80:83], v[0:3], 0
	v_mfma_f32_16x16x32_bf16 v[4:7], v[72:75], v[0:3], 0
	v_mfma_f32_16x16x32_bf16 v[0:3], v[76:79], v[0:3], 0
	s_waitcnt lgkmcnt(8)
	v_mfma_f32_16x16x32_bf16 v[24:27], v[84:87], v[32:35], 0
	v_mfma_f32_16x16x32_bf16 v[28:31], v[88:91], v[32:35], 0
	v_mfma_f32_16x16x32_bf16 v[56:59], v[92:95], v[32:35], 0
	v_mfma_f32_16x16x32_bf16 v[60:63], v[80:83], v[32:35], 0
	v_mfma_f32_16x16x32_bf16 v[64:67], v[72:75], v[32:35], 0
	v_mfma_f32_16x16x32_bf16 v[68:71], v[76:79], v[32:35], 0
	s_waitcnt lgkmcnt(7)
	v_mfma_f32_16x16x32_bf16 v[32:35], v[84:87], v[52:55], 0
	v_mfma_f32_16x16x32_bf16 v[36:39], v[88:91], v[52:55], 0
	v_mfma_f32_16x16x32_bf16 v[40:43], v[92:95], v[52:55], 0
	v_mfma_f32_16x16x32_bf16 v[44:47], v[80:83], v[52:55], 0
	v_mfma_f32_16x16x32_bf16 v[48:51], v[72:75], v[52:55], 0
	v_mfma_f32_16x16x32_bf16 v[52:55], v[76:79], v[52:55], 0
	s_waitcnt lgkmcnt(6)
	v_mfma_f32_16x16x32_bf16 v[96:99], v[84:87], v[116:119], 0
	v_mfma_f32_16x16x32_bf16 v[100:103], v[88:91], v[116:119], 0
	v_mfma_f32_16x16x32_bf16 v[104:107], v[92:95], v[116:119], 0
	v_mfma_f32_16x16x32_bf16 v[108:111], v[80:83], v[116:119], 0
	v_mfma_f32_16x16x32_bf16 v[112:115], v[72:75], v[116:119], 0
	v_cndmask_b32_e64 v72, 0, 1, s[16:17]
	v_cmp_ne_u32_e64 s[70:71], 1, v72
	v_mfma_f32_16x16x32_bf16 v[116:119], v[76:79], v[116:119], 0
	s_cbranch_vccnz .LBB0_381
	ds_read_b128 v[72:75], v239 offset:64
	s_waitcnt lgkmcnt(0)
	v_mfma_f32_16x16x32_bf16 v[20:23], v[120:123], v[72:75], v[20:23]
	v_mfma_f32_16x16x32_bf16 v[16:19], v[124:127], v[72:75], v[16:19]
	v_mfma_f32_16x16x32_bf16 v[12:15], v[128:131], v[72:75], v[12:15]
	v_mfma_f32_16x16x32_bf16 v[8:11], v[132:135], v[72:75], v[8:11]
	v_mfma_f32_16x16x32_bf16 v[4:7], v[136:139], v[72:75], v[4:7]
	v_mfma_f32_16x16x32_bf16 v[0:3], v[140:143], v[72:75], v[0:3]
